# finish phase hand-written with next-item load prefetch (two register buffers)
# speedup vs baseline: 1.0316x; 1.0007x over previous
; DI int otid() { int t = threadIdx.x; asm volatile("" : "+v"(t)); return t; }
; #define ITEM_BEGIN { size_t z_ = 0; asm volatile("" : "+s"(z_)); q.ws = p.ws + z_; sm = smem + osgpr(0); }
; #define PHASE_BEGIN P q = p; { size_t z_ = 0; asm volatile("" : "+s"(z_)); q.ws = p.ws + z_; } unsigned char* sm = smem + osgpr(0); const int b1 = osgpr(bid); (void)sm; (void)b1;
; DI void finish_item(const P& p, int l, int r16) {
;     const bf16_t* S = (const bf16_t*)(p.ws + WS_SBUF);
;     bf16_t* Y = (bf16_t*)(p.ws + WS_YBUF);
;     const bf16_t* O = (const bf16_t*)(p.ws + WS_NBUF);
;     const int tid = otid(); const int row0 = r16 * 16 + (tid >> 7) * 4, u = tid & 127, mx = u >> 6, hh = (u >> 4) & 3, sub = u & 15;
;     const int chn = 128 * hh + 8 * sub;
;     u32x4 ra[4], rb[4], rg[4];
; #pragma unroll
;     for (int k = 0; k < 4; ++k) {
;         ra[k] = __builtin_nontemporal_load((const u32x4*)(O + ((size_t)(mx * 2 + 0) * NROW + row0 + k) * 512 + chn));
;         rb[k] = __builtin_nontemporal_load((const u32x4*)(O + ((size_t)(mx * 2 + 1) * NROW + row0 + k) * 512 + chn));
;         rg[k] = __builtin_nontemporal_load((const u32x4*)(S + (size_t)(row0 + k) * NP + (mx ? C_GDN_G : C_GLA_G) + chn));
;     }
; __global__ __launch_bounds__(512, 2) void mega(P p) {
;     ...
;         { PHASE_BEGIN const int nf = (l == 0 ? NROW : NLAT) / 16; for (int it = b1; it < nf; it += nb) { ITEM_BEGIN finish_item(q, l, it); } }
.LBB0_679:
	s_or_b64 exec, exec, s[0:1]
	s_mov_b64 s[0:1], 0
	s_waitcnt lgkmcnt(0)
	s_barrier
	s_mov_b32 s0, s19
	v_readlane_b32 s4, v254, 26
	v_readlane_b32 s0, v252, 1
	v_readlane_b32 s1, v252, 2
	s_and_b64 s[0:1], s[0:1], exec
	s_movk_i32 s0, 0x240
	v_readlane_b32 s21, v253, 0
	s_cselect_b32 s22, s0, 0x200
	v_readlane_b32 s7, v254, 29
	v_readlane_b32 s36, v254, 39
	s_cmp_ge_i32 s21, s22
	v_readlane_b32 s5, v254, 27
	v_readlane_b32 s6, v254, 28
	s_movk_i32 s7, 0x3800
	s_mov_b64 s[8:9], 0x6c3c000
	s_brev_b32 s10, 60
	v_readlane_b32 s40, v254, 43
	v_readlane_b32 s41, v254, 44
	v_readlane_b32 s48, v254, 51
	v_readlane_b32 s49, v254, 52
	v_readlane_b32 s37, v254, 40
	v_readlane_b32 s38, v254, 41
	v_readlane_b32 s39, v254, 42
	v_readlane_b32 s42, v254, 45
	v_readlane_b32 s43, v254, 46
	v_readlane_b32 s44, v254, 47
	v_readlane_b32 s45, v254, 48
	v_readlane_b32 s46, v254, 49
	v_readlane_b32 s47, v254, 50
	v_readlane_b32 s50, v254, 53
	v_readlane_b32 s51, v254, 54
	s_cbranch_scc1 .LBB0_682
	v_lshrrev_b32_e32 v118, 7, v166
	v_and_b32_e32 v119, 0x7f, v166
	v_lshrrev_b32_e32 v120, 6, v119
	v_and_b32_e32 v121, 63, v119
	v_lshlrev_b32_e32 v121, 4, v121
	v_lshlrev_b32_e32 v104, 24, v120
	v_lshl_add_u32 v104, v120, 21, v104
	v_lshl_add_u32 v104, v118, 12, v104
	v_add_u32_e32 v104, v104, v121
	v_add_u32_e32 v104, 0x483c000, v104
	v_add_u32_e32 v105, 0x900000, v104
	v_mul_u32_u24_e32 v106, 0xe000, v118
	v_lshl_add_u32 v106, v120, 12, v106
	v_add_u32_e32 v106, v106, v121
	v_add_u32_e32 v106, 0x6c3c800, v106
	v_add_u32_e32 v107, 0x3800, v106
	v_add_u32_e32 v108, 0x7000, v106
	v_add_u32_e32 v109, 0xa800, v106
	v_lshlrev_b32_e32 v110, 14, v118
	v_lshl_add_u32 v110, v120, 10, v110
	v_add_u32_e32 v110, v110, v121
	v_add_u32_e32 v110, 0xea3c000, v110
	v_add_u32_e32 v111, 0x1000, v110
	v_add_u32_e32 v112, 0x2000, v110
	v_add_u32_e32 v113, 0x3000, v110
	v_and_b32_e32 v122, 63, v166
	v_xor_b32_e32 v114, 1, v122
	v_lshlrev_b32_e32 v114, 2, v114
	v_xor_b32_e32 v115, 2, v122
	v_lshlrev_b32_e32 v115, 2, v115
	v_xor_b32_e32 v116, 4, v122
	v_lshlrev_b32_e32 v116, 2, v116
	v_xor_b32_e32 v117, 8, v122
	v_lshlrev_b32_e32 v117, 2, v117
	v_and_b32_e32 v123, 15, v119
	v_lshlrev_b32_e32 v123, 5, v123
	s_lshl_b32 s0, s12, 9
	v_add_u32_e32 v123, s0, v123
	v_cmp_eq_u32_e32 vcc, 0, v120
	s_and_saveexec_b64 s[2:3], vcc
	global_load_dwordx4 v[96:99], v123, s[40:41]
	global_load_dwordx4 v[100:103], v123, s[40:41] offset:16
	s_andn2_b64 exec, s[2:3], exec
	global_load_dwordx4 v[96:99], v123, s[48:49]
	global_load_dwordx4 v[100:103], v123, s[48:49] offset:16
	s_mov_b64 exec, s[2:3]
	v_mov_b32_e32 v124, 0x358637bd
	v_mov_b32_e32 v125, 0xbfb8aa3b
	s_mov_b32 s24, s21
	s_lshl_b32 s0, s24, 14
	s_add_u32 s36, s4, s0
	s_addc_u32 s37, s5, 0
	s_mul_i32 s0, s24, 0x38000
	s_add_u32 s38, s4, s0
	s_addc_u32 s39, s5, 0
	global_load_dwordx4 v[0:3], v104, s[36:37] offset:0 nt
	global_load_dwordx4 v[16:19], v105, s[36:37] offset:0 nt
	global_load_dwordx4 v[32:35], v106, s[38:39] nt
	global_load_dwordx4 v[4:7], v104, s[36:37] offset:1024 nt
	global_load_dwordx4 v[20:23], v105, s[36:37] offset:1024 nt
	global_load_dwordx4 v[36:39], v107, s[38:39] nt
	global_load_dwordx4 v[8:11], v104, s[36:37] offset:2048 nt
	global_load_dwordx4 v[24:27], v105, s[36:37] offset:2048 nt
	global_load_dwordx4 v[40:43], v108, s[38:39] nt
	global_load_dwordx4 v[12:15], v104, s[36:37] offset:3072 nt
	global_load_dwordx4 v[28:31], v105, s[36:37] offset:3072 nt
	global_load_dwordx4 v[44:47], v109, s[38:39] nt
	s_add_u32 s7, s24, s6
.Lfin_it0:
	s_cmp_lt_u32 s7, s22
	s_cbranch_scc0 .Lfin_last0
	s_lshl_b32 s0, s7, 14
	s_add_u32 s36, s4, s0
	s_addc_u32 s37, s5, 0
	s_mul_i32 s0, s7, 0x38000
	s_add_u32 s38, s4, s0
	s_addc_u32 s39, s5, 0
	global_load_dwordx4 v[48:51], v104, s[36:37] offset:0 nt
	global_load_dwordx4 v[64:67], v105, s[36:37] offset:0 nt
	global_load_dwordx4 v[80:83], v106, s[38:39] nt
	global_load_dwordx4 v[52:55], v104, s[36:37] offset:1024 nt
	global_load_dwordx4 v[68:71], v105, s[36:37] offset:1024 nt
	global_load_dwordx4 v[84:87], v107, s[38:39] nt
	global_load_dwordx4 v[56:59], v104, s[36:37] offset:2048 nt
	global_load_dwordx4 v[72:75], v105, s[36:37] offset:2048 nt
	global_load_dwordx4 v[88:91], v108, s[38:39] nt
	global_load_dwordx4 v[60:63], v104, s[36:37] offset:3072 nt
	global_load_dwordx4 v[76:79], v105, s[36:37] offset:3072 nt
	global_load_dwordx4 v[92:95], v109, s[38:39] nt
	s_waitcnt vmcnt(12)
	s_branch .Lfin_proc0

; DI void unpack8(u32x4 v, float* o) { o[0] = lo16(v.x); o[1] = hi16(v.x); o[2] = lo16(v.y); o[3] = hi16(v.y); o[4] = lo16(v.z); o[5] = hi16(v.z); o[6] = lo16(v.w); o[7] = hi16(v.w); }
; DI void finish_item(const P& p, int l, int r16) {
;     ...
;     for (int k = 0; k < 4; ++k) {
;         float a[8], b[8], o[8], gt[8];
;         unpack8(ra[k], a); unpack8(rb[k], b); unpack8(rg[k], gt);
;         float ss = 0.f;
; #pragma unroll
;         for (int e = 0; e < 8; ++e) { o[e] = a[e] + b[e]; ss += o[e] * o[e]; }
;         ss += __shfl_xor(ss, 1); ss += __shfl_xor(ss, 2); ss += __shfl_xor(ss, 4); ss += __shfl_xor(ss, 8);
.Lfin_proc0:
	v_and_b32_e32 v118, 0xffff0000, v0
	v_and_b32_e32 v119, 0xffff0000, v16
	v_lshlrev_b32_e32 v0, 16, v0
	v_lshlrev_b32_e32 v120, 16, v16
	v_add_f32_e32 v0, v0, v120
	v_add_f32_e32 v16, v118, v119
	v_mul_f32_e32 v142, v0, v0
	v_fmac_f32_e32 v142, v16, v16
	v_and_b32_e32 v118, 0xffff0000, v1
	v_and_b32_e32 v119, 0xffff0000, v17
	v_lshlrev_b32_e32 v1, 16, v1
	v_lshlrev_b32_e32 v120, 16, v17
	v_add_f32_e32 v1, v1, v120
	v_add_f32_e32 v17, v118, v119
	v_fmac_f32_e32 v142, v1, v1
	v_fmac_f32_e32 v142, v17, v17
	v_and_b32_e32 v118, 0xffff0000, v2
	v_and_b32_e32 v119, 0xffff0000, v18
	v_lshlrev_b32_e32 v2, 16, v2
	v_lshlrev_b32_e32 v120, 16, v18
	v_add_f32_e32 v2, v2, v120
	v_add_f32_e32 v18, v118, v119
	v_fmac_f32_e32 v142, v2, v2
	v_fmac_f32_e32 v142, v18, v18
	v_and_b32_e32 v118, 0xffff0000, v3
	v_and_b32_e32 v119, 0xffff0000, v19
	v_lshlrev_b32_e32 v3, 16, v3
	v_lshlrev_b32_e32 v120, 16, v19
	v_add_f32_e32 v3, v3, v120
	v_add_f32_e32 v19, v118, v119
	v_fmac_f32_e32 v142, v3, v3
	v_fmac_f32_e32 v142, v19, v19
	v_and_b32_e32 v118, 0xffff0000, v4
	v_and_b32_e32 v119, 0xffff0000, v20
	v_lshlrev_b32_e32 v4, 16, v4
	v_lshlrev_b32_e32 v120, 16, v20
	v_add_f32_e32 v4, v4, v120
	v_add_f32_e32 v20, v118, v119
	v_mul_f32_e32 v143, v4, v4
	v_fmac_f32_e32 v143, v20, v20
	v_and_b32_e32 v118, 0xffff0000, v5
	v_and_b32_e32 v119, 0xffff0000, v21
	v_lshlrev_b32_e32 v5, 16, v5
	v_lshlrev_b32_e32 v120, 16, v21
	v_add_f32_e32 v5, v5, v120
	v_add_f32_e32 v21, v118, v119
	v_fmac_f32_e32 v143, v5, v5
	v_fmac_f32_e32 v143, v21, v21
	v_and_b32_e32 v118, 0xffff0000, v6
	v_and_b32_e32 v119, 0xffff0000, v22
	v_lshlrev_b32_e32 v6, 16, v6
	v_lshlrev_b32_e32 v120, 16, v22
	v_add_f32_e32 v6, v6, v120
	v_add_f32_e32 v22, v118, v119
	v_fmac_f32_e32 v143, v6, v6
	v_fmac_f32_e32 v143, v22, v22
	v_and_b32_e32 v118, 0xffff0000, v7
	v_and_b32_e32 v119, 0xffff0000, v23
	v_lshlrev_b32_e32 v7, 16, v7
	v_lshlrev_b32_e32 v120, 16, v23
	v_add_f32_e32 v7, v7, v120
	v_add_f32_e32 v23, v118, v119
	v_fmac_f32_e32 v143, v7, v7
	v_fmac_f32_e32 v143, v23, v23
	v_and_b32_e32 v118, 0xffff0000, v8
	v_and_b32_e32 v119, 0xffff0000, v24
	v_lshlrev_b32_e32 v8, 16, v8
	v_lshlrev_b32_e32 v120, 16, v24
	v_add_f32_e32 v8, v8, v120
	v_add_f32_e32 v24, v118, v119
	v_mul_f32_e32 v144, v8, v8
	v_fmac_f32_e32 v144, v24, v24
	v_and_b32_e32 v118, 0xffff0000, v9
	v_and_b32_e32 v119, 0xffff0000, v25
	v_lshlrev_b32_e32 v9, 16, v9
	v_lshlrev_b32_e32 v120, 16, v25
	v_add_f32_e32 v9, v9, v120
	v_add_f32_e32 v25, v118, v119
	v_fmac_f32_e32 v144, v9, v9
	v_fmac_f32_e32 v144, v25, v25
	v_and_b32_e32 v118, 0xffff0000, v10
	v_and_b32_e32 v119, 0xffff0000, v26
	v_lshlrev_b32_e32 v10, 16, v10
	v_lshlrev_b32_e32 v120, 16, v26
	v_add_f32_e32 v10, v10, v120
	v_add_f32_e32 v26, v118, v119
	v_fmac_f32_e32 v144, v10, v10
	v_fmac_f32_e32 v144, v26, v26
	v_and_b32_e32 v118, 0xffff0000, v11
	v_and_b32_e32 v119, 0xffff0000, v27
	v_lshlrev_b32_e32 v11, 16, v11
	v_lshlrev_b32_e32 v120, 16, v27
	v_add_f32_e32 v11, v11, v120
	v_add_f32_e32 v27, v118, v119
	v_fmac_f32_e32 v144, v11, v11
	v_fmac_f32_e32 v144, v27, v27
	v_and_b32_e32 v118, 0xffff0000, v12
	v_and_b32_e32 v119, 0xffff0000, v28
	v_lshlrev_b32_e32 v12, 16, v12
	v_lshlrev_b32_e32 v120, 16, v28
	v_add_f32_e32 v12, v12, v120
	v_add_f32_e32 v28, v118, v119
	v_mul_f32_e32 v145, v12, v12
	v_fmac_f32_e32 v145, v28, v28
	v_and_b32_e32 v118, 0xffff0000, v13
	v_and_b32_e32 v119, 0xffff0000, v29
	v_lshlrev_b32_e32 v13, 16, v13
	v_lshlrev_b32_e32 v120, 16, v29
	v_add_f32_e32 v13, v13, v120
	v_add_f32_e32 v29, v118, v119
	v_fmac_f32_e32 v145, v13, v13
	v_fmac_f32_e32 v145, v29, v29
	v_and_b32_e32 v118, 0xffff0000, v14
	v_and_b32_e32 v119, 0xffff0000, v30
	v_lshlrev_b32_e32 v14, 16, v14
	v_lshlrev_b32_e32 v120, 16, v30
	v_add_f32_e32 v14, v14, v120
	v_add_f32_e32 v30, v118, v119
	v_fmac_f32_e32 v145, v14, v14
	v_fmac_f32_e32 v145, v30, v30
	v_and_b32_e32 v118, 0xffff0000, v15
	v_and_b32_e32 v119, 0xffff0000, v31
	v_lshlrev_b32_e32 v15, 16, v15
	v_lshlrev_b32_e32 v120, 16, v31
	v_add_f32_e32 v15, v15, v120
	v_add_f32_e32 v31, v118, v119
	v_fmac_f32_e32 v145, v15, v15
	v_fmac_f32_e32 v145, v31, v31
	ds_bpermute_b32 v146, v114, v142
	ds_bpermute_b32 v147, v114, v143
	ds_bpermute_b32 v148, v114, v144
	ds_bpermute_b32 v149, v114, v145
	s_waitcnt lgkmcnt(3)
	v_add_f32_e32 v142, v142, v146
	s_waitcnt lgkmcnt(2)
	v_add_f32_e32 v143, v143, v147
	s_waitcnt lgkmcnt(1)
	v_add_f32_e32 v144, v144, v148
	s_waitcnt lgkmcnt(0)
	v_add_f32_e32 v145, v145, v149
	ds_bpermute_b32 v146, v115, v142
	ds_bpermute_b32 v147, v115, v143
	ds_bpermute_b32 v148, v115, v144
	ds_bpermute_b32 v149, v115, v145
	s_waitcnt lgkmcnt(3)
	v_add_f32_e32 v142, v142, v146
	s_waitcnt lgkmcnt(2)
	v_add_f32_e32 v143, v143, v147
	s_waitcnt lgkmcnt(1)
	v_add_f32_e32 v144, v144, v148
	s_waitcnt lgkmcnt(0)
	v_add_f32_e32 v145, v145, v149
	ds_bpermute_b32 v146, v116, v142
	ds_bpermute_b32 v147, v116, v143
	ds_bpermute_b32 v148, v116, v144
	ds_bpermute_b32 v149, v116, v145
	s_waitcnt lgkmcnt(3)
	v_add_f32_e32 v142, v142, v146
	s_waitcnt lgkmcnt(2)
	v_add_f32_e32 v143, v143, v147
	s_waitcnt lgkmcnt(1)
	v_add_f32_e32 v144, v144, v148
	s_waitcnt lgkmcnt(0)
	v_add_f32_e32 v145, v145, v149
	ds_bpermute_b32 v146, v117, v142
	ds_bpermute_b32 v147, v117, v143
	ds_bpermute_b32 v148, v117, v144
	ds_bpermute_b32 v149, v117, v145
	s_waitcnt lgkmcnt(3)
	v_add_f32_e32 v142, v142, v146
	s_waitcnt lgkmcnt(2)
	v_add_f32_e32 v143, v143, v147
	s_waitcnt lgkmcnt(1)
	v_add_f32_e32 v144, v144, v148
	s_waitcnt lgkmcnt(0)
; DI u32x4 pack8(const float* o) { u32x4 r; r.x = pk2(o[0], o[1]); r.y = pk2(o[2], o[3]); r.z = pk2(o[4], o[5]); r.w = pk2(o[6], o[7]); return r; }
; DI float siluf(float x) { return x * __builtin_amdgcn_rcpf(1.f + __expf(-x)); }
; DI void finish_item(const P& p, int l, int r16) {
;     ...
;         const float rstd = rsqrtf(ss * (1.f / 128.f) + 1e-6f);
; #pragma unroll
;         for (int e = 0; e < 8; ++e) o[e] = o[e] * rstd * (e < 4 ? nw0[e & 3] : nw1[e & 3]) * siluf(gt[e]);
;         *(u32x4*)(Y + (size_t)(row0 + k) * DM + 512 * mx + chn) = pack8(o);
	v_add_f32_e32 v145, v145, v149
	v_fmamk_f32 v142, v142, 0x3c000000, v124
	v_fmamk_f32 v143, v143, 0x3c000000, v124
	v_fmamk_f32 v144, v144, 0x3c000000, v124
	v_fmamk_f32 v145, v145, 0x3c000000, v124
	v_rsq_f32_e32 v150, v142
	v_rsq_f32_e32 v151, v143
	v_rsq_f32_e32 v152, v144
	v_rsq_f32_e32 v153, v145
	s_lshl_b32 s0, s24, 16
	s_add_u32 s42, s4, s0
	s_addc_u32 s43, s5, 0
	v_lshlrev_b32_e32 v118, 16, v32
	v_and_b32_e32 v119, 0xffff0000, v32
	v_mul_f32_e32 v120, v125, v118
	v_mul_f32_e32 v121, v125, v119
	v_exp_f32_e32 v120, v120
	v_exp_f32_e32 v121, v121
	v_mul_f32_e32 v0, v0, v150
	v_add_f32_e32 v120, 1.0, v120
	v_add_f32_e32 v121, 1.0, v121
	v_rcp_f32_e32 v120, v120
	v_rcp_f32_e32 v121, v121
	v_mul_f32_e32 v16, v16, v150
	v_mul_f32_e32 v0, v0, v96
	v_mul_f32_e32 v118, v118, v120
	v_mul_f32_e32 v119, v119, v121
	v_mul_f32_e32 v16, v16, v97
	v_mul_f32_e32 v0, v0, v118
	v_mul_f32_e32 v16, v16, v119
	v_cvt_pk_bf16_f32 v154, v0, v16
	v_lshlrev_b32_e32 v118, 16, v33
	v_and_b32_e32 v119, 0xffff0000, v33
	v_mul_f32_e32 v120, v125, v118
	v_mul_f32_e32 v121, v125, v119
	v_exp_f32_e32 v120, v120
	v_exp_f32_e32 v121, v121
	v_mul_f32_e32 v1, v1, v150
	v_add_f32_e32 v120, 1.0, v120
	v_add_f32_e32 v121, 1.0, v121
	v_rcp_f32_e32 v120, v120
	v_rcp_f32_e32 v121, v121
	v_mul_f32_e32 v17, v17, v150
	v_mul_f32_e32 v1, v1, v98
	v_mul_f32_e32 v118, v118, v120
	v_mul_f32_e32 v119, v119, v121
	v_mul_f32_e32 v17, v17, v99
	v_mul_f32_e32 v1, v1, v118
	v_mul_f32_e32 v17, v17, v119
	v_cvt_pk_bf16_f32 v155, v1, v17
	v_lshlrev_b32_e32 v118, 16, v34
	v_and_b32_e32 v119, 0xffff0000, v34
	v_mul_f32_e32 v120, v125, v118
	v_mul_f32_e32 v121, v125, v119
	v_exp_f32_e32 v120, v120
	v_exp_f32_e32 v121, v121
	v_mul_f32_e32 v2, v2, v150
	v_add_f32_e32 v120, 1.0, v120
	v_add_f32_e32 v121, 1.0, v121
	v_rcp_f32_e32 v120, v120
	v_rcp_f32_e32 v121, v121
	v_mul_f32_e32 v18, v18, v150
	v_mul_f32_e32 v2, v2, v100
	v_mul_f32_e32 v118, v118, v120
	v_mul_f32_e32 v119, v119, v121
	v_mul_f32_e32 v18, v18, v101
	v_mul_f32_e32 v2, v2, v118
	v_mul_f32_e32 v18, v18, v119
	v_cvt_pk_bf16_f32 v156, v2, v18
	v_lshlrev_b32_e32 v118, 16, v35
	v_and_b32_e32 v119, 0xffff0000, v35
	v_mul_f32_e32 v120, v125, v118
	v_mul_f32_e32 v121, v125, v119
	v_exp_f32_e32 v120, v120
	v_exp_f32_e32 v121, v121
	v_mul_f32_e32 v3, v3, v150
	v_add_f32_e32 v120, 1.0, v120
	v_add_f32_e32 v121, 1.0, v121
	v_rcp_f32_e32 v120, v120
	v_rcp_f32_e32 v121, v121
	v_mul_f32_e32 v19, v19, v150
	v_mul_f32_e32 v3, v3, v102
	v_mul_f32_e32 v118, v118, v120
	v_mul_f32_e32 v119, v119, v121
	v_mul_f32_e32 v19, v19, v103
	v_mul_f32_e32 v3, v3, v118
	v_mul_f32_e32 v19, v19, v119
	v_cvt_pk_bf16_f32 v157, v3, v19
	global_store_dwordx4 v110, v[154:157], s[42:43]
	v_lshlrev_b32_e32 v118, 16, v36
	v_and_b32_e32 v119, 0xffff0000, v36
	v_mul_f32_e32 v120, v125, v118
	v_mul_f32_e32 v121, v125, v119
	v_exp_f32_e32 v120, v120
	v_exp_f32_e32 v121, v121
	v_mul_f32_e32 v4, v4, v151
	v_add_f32_e32 v120, 1.0, v120
	v_add_f32_e32 v121, 1.0, v121
	v_rcp_f32_e32 v120, v120
	v_rcp_f32_e32 v121, v121
	v_mul_f32_e32 v20, v20, v151
	v_mul_f32_e32 v4, v4, v96
	v_mul_f32_e32 v118, v118, v120
	v_mul_f32_e32 v119, v119, v121
	v_mul_f32_e32 v20, v20, v97
	v_mul_f32_e32 v4, v4, v118
	v_mul_f32_e32 v20, v20, v119
	v_cvt_pk_bf16_f32 v158, v4, v20
	v_lshlrev_b32_e32 v118, 16, v37
	v_and_b32_e32 v119, 0xffff0000, v37
	v_mul_f32_e32 v120, v125, v118
	v_mul_f32_e32 v121, v125, v119
	v_exp_f32_e32 v120, v120
	v_exp_f32_e32 v121, v121
	v_mul_f32_e32 v5, v5, v151
	v_add_f32_e32 v120, 1.0, v120
	v_add_f32_e32 v121, 1.0, v121
	v_rcp_f32_e32 v120, v120
	v_rcp_f32_e32 v121, v121
	v_mul_f32_e32 v21, v21, v151
	v_mul_f32_e32 v5, v5, v98
	v_mul_f32_e32 v118, v118, v120
	v_mul_f32_e32 v119, v119, v121
	v_mul_f32_e32 v21, v21, v99
	v_mul_f32_e32 v5, v5, v118
	v_mul_f32_e32 v21, v21, v119
	v_cvt_pk_bf16_f32 v159, v5, v21
	v_lshlrev_b32_e32 v118, 16, v38
	v_and_b32_e32 v119, 0xffff0000, v38
	v_mul_f32_e32 v120, v125, v118
	v_mul_f32_e32 v121, v125, v119
	v_exp_f32_e32 v120, v120
	v_exp_f32_e32 v121, v121
	v_mul_f32_e32 v6, v6, v151
	v_add_f32_e32 v120, 1.0, v120
	v_add_f32_e32 v121, 1.0, v121
	v_rcp_f32_e32 v120, v120
	v_rcp_f32_e32 v121, v121
	v_mul_f32_e32 v22, v22, v151
	v_mul_f32_e32 v6, v6, v100
	v_mul_f32_e32 v118, v118, v120
	v_mul_f32_e32 v119, v119, v121
	v_mul_f32_e32 v22, v22, v101
	v_mul_f32_e32 v6, v6, v118
	v_mul_f32_e32 v22, v22, v119
	v_cvt_pk_bf16_f32 v160, v6, v22
	v_lshlrev_b32_e32 v118, 16, v39
	v_and_b32_e32 v119, 0xffff0000, v39
	v_mul_f32_e32 v120, v125, v118
	v_mul_f32_e32 v121, v125, v119
	v_exp_f32_e32 v120, v120
	v_exp_f32_e32 v121, v121
	v_mul_f32_e32 v7, v7, v151
	v_add_f32_e32 v120, 1.0, v120
	v_add_f32_e32 v121, 1.0, v121
	v_rcp_f32_e32 v120, v120
	v_rcp_f32_e32 v121, v121
	v_mul_f32_e32 v23, v23, v151
	v_mul_f32_e32 v7, v7, v102
	v_mul_f32_e32 v118, v118, v120
	v_mul_f32_e32 v119, v119, v121
	v_mul_f32_e32 v23, v23, v103
	v_mul_f32_e32 v7, v7, v118
	v_mul_f32_e32 v23, v23, v119
	v_cvt_pk_bf16_f32 v161, v7, v23
	global_store_dwordx4 v111, v[158:161], s[42:43]
	v_lshlrev_b32_e32 v118, 16, v40
	v_and_b32_e32 v119, 0xffff0000, v40
	v_mul_f32_e32 v120, v125, v118
	v_mul_f32_e32 v121, v125, v119
	v_exp_f32_e32 v120, v120
	v_exp_f32_e32 v121, v121
	v_mul_f32_e32 v8, v8, v152
	v_add_f32_e32 v120, 1.0, v120
	v_add_f32_e32 v121, 1.0, v121
	v_rcp_f32_e32 v120, v120
	v_rcp_f32_e32 v121, v121
; DI u32x4 pack8(const float* o) { u32x4 r; r.x = pk2(o[0], o[1]); r.y = pk2(o[2], o[3]); r.z = pk2(o[4], o[5]); r.w = pk2(o[6], o[7]); return r; }
; DI float siluf(float x) { return x * __builtin_amdgcn_rcpf(1.f + __expf(-x)); }
; #define ITEM_BEGIN { size_t z_ = 0; asm volatile("" : "+s"(z_)); q.ws = p.ws + z_; sm = smem + osgpr(0); }
; #define PHASE_BEGIN P q = p; { size_t z_ = 0; asm volatile("" : "+s"(z_)); q.ws = p.ws + z_; } unsigned char* sm = smem + osgpr(0); const int b1 = osgpr(bid); (void)sm; (void)b1;
; DI void finish_item(const P& p, int l, int r16) {
;     ...
;         for (int e = 0; e < 8; ++e) o[e] = o[e] * rstd * (e < 4 ? nw0[e & 3] : nw1[e & 3]) * siluf(gt[e]);
;         *(u32x4*)(Y + (size_t)(row0 + k) * DM + 512 * mx + chn) = pack8(o);
;     }
; }
; __global__ __launch_bounds__(512, 2) void mega(P p) {
;     ...
;         { PHASE_BEGIN const int nf = (l == 0 ? NROW : NLAT) / 16; for (int it = b1; it < nf; it += nb) { ITEM_BEGIN finish_item(q, l, it); } }
	v_mul_f32_e32 v24, v24, v152
	v_mul_f32_e32 v8, v8, v96
	v_mul_f32_e32 v118, v118, v120
	v_mul_f32_e32 v119, v119, v121
	v_mul_f32_e32 v24, v24, v97
	v_mul_f32_e32 v8, v8, v118
	v_mul_f32_e32 v24, v24, v119
	v_cvt_pk_bf16_f32 v154, v8, v24
	v_lshlrev_b32_e32 v118, 16, v41
	v_and_b32_e32 v119, 0xffff0000, v41
	v_mul_f32_e32 v120, v125, v118
	v_mul_f32_e32 v121, v125, v119
	v_exp_f32_e32 v120, v120
	v_exp_f32_e32 v121, v121
	v_mul_f32_e32 v9, v9, v152
	v_add_f32_e32 v120, 1.0, v120
	v_add_f32_e32 v121, 1.0, v121
	v_rcp_f32_e32 v120, v120
	v_rcp_f32_e32 v121, v121
	v_mul_f32_e32 v25, v25, v152
	v_mul_f32_e32 v9, v9, v98
	v_mul_f32_e32 v118, v118, v120
	v_mul_f32_e32 v119, v119, v121
	v_mul_f32_e32 v25, v25, v99
	v_mul_f32_e32 v9, v9, v118
	v_mul_f32_e32 v25, v25, v119
	v_cvt_pk_bf16_f32 v155, v9, v25
	v_lshlrev_b32_e32 v118, 16, v42
	v_and_b32_e32 v119, 0xffff0000, v42
	v_mul_f32_e32 v120, v125, v118
	v_mul_f32_e32 v121, v125, v119
	v_exp_f32_e32 v120, v120
	v_exp_f32_e32 v121, v121
	v_mul_f32_e32 v10, v10, v152
	v_add_f32_e32 v120, 1.0, v120
	v_add_f32_e32 v121, 1.0, v121
	v_rcp_f32_e32 v120, v120
	v_rcp_f32_e32 v121, v121
	v_mul_f32_e32 v26, v26, v152
	v_mul_f32_e32 v10, v10, v100
	v_mul_f32_e32 v118, v118, v120
	v_mul_f32_e32 v119, v119, v121
	v_mul_f32_e32 v26, v26, v101
	v_mul_f32_e32 v10, v10, v118
	v_mul_f32_e32 v26, v26, v119
	v_cvt_pk_bf16_f32 v156, v10, v26
	v_lshlrev_b32_e32 v118, 16, v43
	v_and_b32_e32 v119, 0xffff0000, v43
	v_mul_f32_e32 v120, v125, v118
	v_mul_f32_e32 v121, v125, v119
	v_exp_f32_e32 v120, v120
	v_exp_f32_e32 v121, v121
	v_mul_f32_e32 v11, v11, v152
	v_add_f32_e32 v120, 1.0, v120
	v_add_f32_e32 v121, 1.0, v121
	v_rcp_f32_e32 v120, v120
	v_rcp_f32_e32 v121, v121
	v_mul_f32_e32 v27, v27, v152
	v_mul_f32_e32 v11, v11, v102
	v_mul_f32_e32 v118, v118, v120
	v_mul_f32_e32 v119, v119, v121
	v_mul_f32_e32 v27, v27, v103
	v_mul_f32_e32 v11, v11, v118
	v_mul_f32_e32 v27, v27, v119
	v_cvt_pk_bf16_f32 v157, v11, v27
	global_store_dwordx4 v112, v[154:157], s[42:43]
	v_lshlrev_b32_e32 v118, 16, v44
	v_and_b32_e32 v119, 0xffff0000, v44
	v_mul_f32_e32 v120, v125, v118
	v_mul_f32_e32 v121, v125, v119
	v_exp_f32_e32 v120, v120
	v_exp_f32_e32 v121, v121
	v_mul_f32_e32 v12, v12, v153
	v_add_f32_e32 v120, 1.0, v120
	v_add_f32_e32 v121, 1.0, v121
	v_rcp_f32_e32 v120, v120
	v_rcp_f32_e32 v121, v121
	v_mul_f32_e32 v28, v28, v153
	v_mul_f32_e32 v12, v12, v96
	v_mul_f32_e32 v118, v118, v120
	v_mul_f32_e32 v119, v119, v121
	v_mul_f32_e32 v28, v28, v97
	v_mul_f32_e32 v12, v12, v118
	v_mul_f32_e32 v28, v28, v119
	v_cvt_pk_bf16_f32 v158, v12, v28
	v_lshlrev_b32_e32 v118, 16, v45
	v_and_b32_e32 v119, 0xffff0000, v45
	v_mul_f32_e32 v120, v125, v118
	v_mul_f32_e32 v121, v125, v119
	v_exp_f32_e32 v120, v120
	v_exp_f32_e32 v121, v121
	v_mul_f32_e32 v13, v13, v153
	v_add_f32_e32 v120, 1.0, v120
	v_add_f32_e32 v121, 1.0, v121
	v_rcp_f32_e32 v120, v120
	v_rcp_f32_e32 v121, v121
	v_mul_f32_e32 v29, v29, v153
	v_mul_f32_e32 v13, v13, v98
	v_mul_f32_e32 v118, v118, v120
	v_mul_f32_e32 v119, v119, v121
	v_mul_f32_e32 v29, v29, v99
	v_mul_f32_e32 v13, v13, v118
	v_mul_f32_e32 v29, v29, v119
	v_cvt_pk_bf16_f32 v159, v13, v29
	v_lshlrev_b32_e32 v118, 16, v46
	v_and_b32_e32 v119, 0xffff0000, v46
	v_mul_f32_e32 v120, v125, v118
	v_mul_f32_e32 v121, v125, v119
	v_exp_f32_e32 v120, v120
	v_exp_f32_e32 v121, v121
	v_mul_f32_e32 v14, v14, v153
	v_add_f32_e32 v120, 1.0, v120
	v_add_f32_e32 v121, 1.0, v121
	v_rcp_f32_e32 v120, v120
	v_rcp_f32_e32 v121, v121
	v_mul_f32_e32 v30, v30, v153
	v_mul_f32_e32 v14, v14, v100
	v_mul_f32_e32 v118, v118, v120
	v_mul_f32_e32 v119, v119, v121
	v_mul_f32_e32 v30, v30, v101
	v_mul_f32_e32 v14, v14, v118
	v_mul_f32_e32 v30, v30, v119
	v_cvt_pk_bf16_f32 v160, v14, v30
	v_lshlrev_b32_e32 v118, 16, v47
	v_and_b32_e32 v119, 0xffff0000, v47
	v_mul_f32_e32 v120, v125, v118
	v_mul_f32_e32 v121, v125, v119
	v_exp_f32_e32 v120, v120
	v_exp_f32_e32 v121, v121
	v_mul_f32_e32 v15, v15, v153
	v_add_f32_e32 v120, 1.0, v120
	v_add_f32_e32 v121, 1.0, v121
	v_rcp_f32_e32 v120, v120
	v_rcp_f32_e32 v121, v121
	v_mul_f32_e32 v31, v31, v153
	v_mul_f32_e32 v15, v15, v102
	v_mul_f32_e32 v118, v118, v120
	v_mul_f32_e32 v119, v119, v121
	v_mul_f32_e32 v31, v31, v103
	v_mul_f32_e32 v15, v15, v118
	v_mul_f32_e32 v31, v31, v119
	v_cvt_pk_bf16_f32 v161, v15, v31
	global_store_dwordx4 v113, v[158:161], s[42:43]
	s_cmp_lt_u32 s7, s22
	s_cbranch_scc0 .Lfin_done
	s_mov_b32 s24, s7
	s_add_u32 s7, s7, s6
.Lfin_it1:
	s_cmp_lt_u32 s7, s22
	s_cbranch_scc0 .Lfin_last1
	s_lshl_b32 s0, s7, 14
	s_add_u32 s36, s4, s0
	s_addc_u32 s37, s5, 0
	s_mul_i32 s0, s7, 0x38000
	s_add_u32 s38, s4, s0
	s_addc_u32 s39, s5, 0
	global_load_dwordx4 v[0:3], v104, s[36:37] offset:0 nt
	global_load_dwordx4 v[16:19], v105, s[36:37] offset:0 nt
	global_load_dwordx4 v[32:35], v106, s[38:39] nt
	global_load_dwordx4 v[4:7], v104, s[36:37] offset:1024 nt
	global_load_dwordx4 v[20:23], v105, s[36:37] offset:1024 nt
	global_load_dwordx4 v[36:39], v107, s[38:39] nt
	global_load_dwordx4 v[8:11], v104, s[36:37] offset:2048 nt
	global_load_dwordx4 v[24:27], v105, s[36:37] offset:2048 nt
	global_load_dwordx4 v[40:43], v108, s[38:39] nt
	global_load_dwordx4 v[12:15], v104, s[36:37] offset:3072 nt
	global_load_dwordx4 v[28:31], v105, s[36:37] offset:3072 nt
	global_load_dwordx4 v[44:47], v109, s[38:39] nt
	s_waitcnt vmcnt(12)
	s_branch .Lfin_proc1

; DI void unpack8(u32x4 v, float* o) { o[0] = lo16(v.x); o[1] = hi16(v.x); o[2] = lo16(v.y); o[3] = hi16(v.y); o[4] = lo16(v.z); o[5] = hi16(v.z); o[6] = lo16(v.w); o[7] = hi16(v.w); }
; DI void finish_item(const P& p, int l, int r16) {
;     ...
;     for (int k = 0; k < 4; ++k) {
;         float a[8], b[8], o[8], gt[8];
;         unpack8(ra[k], a); unpack8(rb[k], b); unpack8(rg[k], gt);
;         float ss = 0.f;
; #pragma unroll
;         for (int e = 0; e < 8; ++e) { o[e] = a[e] + b[e]; ss += o[e] * o[e]; }
;         ss += __shfl_xor(ss, 1); ss += __shfl_xor(ss, 2); ss += __shfl_xor(ss, 4); ss += __shfl_xor(ss, 8);
.Lfin_proc1:
	v_and_b32_e32 v118, 0xffff0000, v48
	v_and_b32_e32 v119, 0xffff0000, v64
	v_lshlrev_b32_e32 v48, 16, v48
	v_lshlrev_b32_e32 v120, 16, v64
	v_add_f32_e32 v48, v48, v120
	v_add_f32_e32 v64, v118, v119
	v_mul_f32_e32 v142, v48, v48
	v_fmac_f32_e32 v142, v64, v64
	v_and_b32_e32 v118, 0xffff0000, v49
	v_and_b32_e32 v119, 0xffff0000, v65
	v_lshlrev_b32_e32 v49, 16, v49
	v_lshlrev_b32_e32 v120, 16, v65
	v_add_f32_e32 v49, v49, v120
	v_add_f32_e32 v65, v118, v119
	v_fmac_f32_e32 v142, v49, v49
	v_fmac_f32_e32 v142, v65, v65
	v_and_b32_e32 v118, 0xffff0000, v50
	v_and_b32_e32 v119, 0xffff0000, v66
	v_lshlrev_b32_e32 v50, 16, v50
	v_lshlrev_b32_e32 v120, 16, v66
	v_add_f32_e32 v50, v50, v120
	v_add_f32_e32 v66, v118, v119
	v_fmac_f32_e32 v142, v50, v50
	v_fmac_f32_e32 v142, v66, v66
	v_and_b32_e32 v118, 0xffff0000, v51
	v_and_b32_e32 v119, 0xffff0000, v67
	v_lshlrev_b32_e32 v51, 16, v51
	v_lshlrev_b32_e32 v120, 16, v67
	v_add_f32_e32 v51, v51, v120
	v_add_f32_e32 v67, v118, v119
	v_fmac_f32_e32 v142, v51, v51
	v_fmac_f32_e32 v142, v67, v67
	v_and_b32_e32 v118, 0xffff0000, v52
	v_and_b32_e32 v119, 0xffff0000, v68
	v_lshlrev_b32_e32 v52, 16, v52
	v_lshlrev_b32_e32 v120, 16, v68
	v_add_f32_e32 v52, v52, v120
	v_add_f32_e32 v68, v118, v119
	v_mul_f32_e32 v143, v52, v52
	v_fmac_f32_e32 v143, v68, v68
	v_and_b32_e32 v118, 0xffff0000, v53
	v_and_b32_e32 v119, 0xffff0000, v69
	v_lshlrev_b32_e32 v53, 16, v53
	v_lshlrev_b32_e32 v120, 16, v69
	v_add_f32_e32 v53, v53, v120
	v_add_f32_e32 v69, v118, v119
	v_fmac_f32_e32 v143, v53, v53
	v_fmac_f32_e32 v143, v69, v69
	v_and_b32_e32 v118, 0xffff0000, v54
	v_and_b32_e32 v119, 0xffff0000, v70
	v_lshlrev_b32_e32 v54, 16, v54
	v_lshlrev_b32_e32 v120, 16, v70
	v_add_f32_e32 v54, v54, v120
	v_add_f32_e32 v70, v118, v119
	v_fmac_f32_e32 v143, v54, v54
	v_fmac_f32_e32 v143, v70, v70
	v_and_b32_e32 v118, 0xffff0000, v55
	v_and_b32_e32 v119, 0xffff0000, v71
	v_lshlrev_b32_e32 v55, 16, v55
	v_lshlrev_b32_e32 v120, 16, v71
	v_add_f32_e32 v55, v55, v120
	v_add_f32_e32 v71, v118, v119
	v_fmac_f32_e32 v143, v55, v55
	v_fmac_f32_e32 v143, v71, v71
	v_and_b32_e32 v118, 0xffff0000, v56
	v_and_b32_e32 v119, 0xffff0000, v72
	v_lshlrev_b32_e32 v56, 16, v56
	v_lshlrev_b32_e32 v120, 16, v72
	v_add_f32_e32 v56, v56, v120
	v_add_f32_e32 v72, v118, v119
	v_mul_f32_e32 v144, v56, v56
	v_fmac_f32_e32 v144, v72, v72
	v_and_b32_e32 v118, 0xffff0000, v57
	v_and_b32_e32 v119, 0xffff0000, v73
	v_lshlrev_b32_e32 v57, 16, v57
	v_lshlrev_b32_e32 v120, 16, v73
	v_add_f32_e32 v57, v57, v120
	v_add_f32_e32 v73, v118, v119
	v_fmac_f32_e32 v144, v57, v57
	v_fmac_f32_e32 v144, v73, v73
	v_and_b32_e32 v118, 0xffff0000, v58
	v_and_b32_e32 v119, 0xffff0000, v74
	v_lshlrev_b32_e32 v58, 16, v58
	v_lshlrev_b32_e32 v120, 16, v74
	v_add_f32_e32 v58, v58, v120
	v_add_f32_e32 v74, v118, v119
	v_fmac_f32_e32 v144, v58, v58
	v_fmac_f32_e32 v144, v74, v74
	v_and_b32_e32 v118, 0xffff0000, v59
	v_and_b32_e32 v119, 0xffff0000, v75
	v_lshlrev_b32_e32 v59, 16, v59
	v_lshlrev_b32_e32 v120, 16, v75
	v_add_f32_e32 v59, v59, v120
	v_add_f32_e32 v75, v118, v119
	v_fmac_f32_e32 v144, v59, v59
	v_fmac_f32_e32 v144, v75, v75
	v_and_b32_e32 v118, 0xffff0000, v60
	v_and_b32_e32 v119, 0xffff0000, v76
	v_lshlrev_b32_e32 v60, 16, v60
	v_lshlrev_b32_e32 v120, 16, v76
	v_add_f32_e32 v60, v60, v120
	v_add_f32_e32 v76, v118, v119
	v_mul_f32_e32 v145, v60, v60
	v_fmac_f32_e32 v145, v76, v76
	v_and_b32_e32 v118, 0xffff0000, v61
	v_and_b32_e32 v119, 0xffff0000, v77
	v_lshlrev_b32_e32 v61, 16, v61
	v_lshlrev_b32_e32 v120, 16, v77
	v_add_f32_e32 v61, v61, v120
	v_add_f32_e32 v77, v118, v119
	v_fmac_f32_e32 v145, v61, v61
	v_fmac_f32_e32 v145, v77, v77
	v_and_b32_e32 v118, 0xffff0000, v62
	v_and_b32_e32 v119, 0xffff0000, v78
	v_lshlrev_b32_e32 v62, 16, v62
	v_lshlrev_b32_e32 v120, 16, v78
	v_add_f32_e32 v62, v62, v120
	v_add_f32_e32 v78, v118, v119
	v_fmac_f32_e32 v145, v62, v62
	v_fmac_f32_e32 v145, v78, v78
	v_and_b32_e32 v118, 0xffff0000, v63
	v_and_b32_e32 v119, 0xffff0000, v79
	v_lshlrev_b32_e32 v63, 16, v63
	v_lshlrev_b32_e32 v120, 16, v79
	v_add_f32_e32 v63, v63, v120
	v_add_f32_e32 v79, v118, v119
	v_fmac_f32_e32 v145, v63, v63
	v_fmac_f32_e32 v145, v79, v79
	ds_bpermute_b32 v146, v114, v142
	ds_bpermute_b32 v147, v114, v143
	ds_bpermute_b32 v148, v114, v144
	ds_bpermute_b32 v149, v114, v145
	s_waitcnt lgkmcnt(3)
	v_add_f32_e32 v142, v142, v146
	s_waitcnt lgkmcnt(2)
	v_add_f32_e32 v143, v143, v147
	s_waitcnt lgkmcnt(1)
	v_add_f32_e32 v144, v144, v148
	s_waitcnt lgkmcnt(0)
	v_add_f32_e32 v145, v145, v149
	ds_bpermute_b32 v146, v115, v142
	ds_bpermute_b32 v147, v115, v143
	ds_bpermute_b32 v148, v115, v144
	ds_bpermute_b32 v149, v115, v145
	s_waitcnt lgkmcnt(3)
	v_add_f32_e32 v142, v142, v146
	s_waitcnt lgkmcnt(2)
	v_add_f32_e32 v143, v143, v147
	s_waitcnt lgkmcnt(1)
	v_add_f32_e32 v144, v144, v148
	s_waitcnt lgkmcnt(0)
	v_add_f32_e32 v145, v145, v149
	ds_bpermute_b32 v146, v116, v142
	ds_bpermute_b32 v147, v116, v143
	ds_bpermute_b32 v148, v116, v144
	ds_bpermute_b32 v149, v116, v145
	s_waitcnt lgkmcnt(3)
	v_add_f32_e32 v142, v142, v146
	s_waitcnt lgkmcnt(2)
	v_add_f32_e32 v143, v143, v147
	s_waitcnt lgkmcnt(1)
	v_add_f32_e32 v144, v144, v148
	s_waitcnt lgkmcnt(0)
	v_add_f32_e32 v145, v145, v149
	ds_bpermute_b32 v146, v117, v142
	ds_bpermute_b32 v147, v117, v143
	ds_bpermute_b32 v148, v117, v144
	ds_bpermute_b32 v149, v117, v145
	s_waitcnt lgkmcnt(3)
	v_add_f32_e32 v142, v142, v146
	s_waitcnt lgkmcnt(2)
	v_add_f32_e32 v143, v143, v147
	s_waitcnt lgkmcnt(1)
	v_add_f32_e32 v144, v144, v148
	s_waitcnt lgkmcnt(0)
; DI u32x4 pack8(const float* o) { u32x4 r; r.x = pk2(o[0], o[1]); r.y = pk2(o[2], o[3]); r.z = pk2(o[4], o[5]); r.w = pk2(o[6], o[7]); return r; }
; DI float siluf(float x) { return x * __builtin_amdgcn_rcpf(1.f + __expf(-x)); }
; DI void finish_item(const P& p, int l, int r16) {
;     ...
;         const float rstd = rsqrtf(ss * (1.f / 128.f) + 1e-6f);
; #pragma unroll
;         for (int e = 0; e < 8; ++e) o[e] = o[e] * rstd * (e < 4 ? nw0[e & 3] : nw1[e & 3]) * siluf(gt[e]);
;         *(u32x4*)(Y + (size_t)(row0 + k) * DM + 512 * mx + chn) = pack8(o);
	v_add_f32_e32 v145, v145, v149
	v_fmamk_f32 v142, v142, 0x3c000000, v124
	v_fmamk_f32 v143, v143, 0x3c000000, v124
	v_fmamk_f32 v144, v144, 0x3c000000, v124
	v_fmamk_f32 v145, v145, 0x3c000000, v124
	v_rsq_f32_e32 v150, v142
	v_rsq_f32_e32 v151, v143
	v_rsq_f32_e32 v152, v144
	v_rsq_f32_e32 v153, v145
	s_lshl_b32 s0, s24, 16
	s_add_u32 s42, s4, s0
	s_addc_u32 s43, s5, 0
	v_lshlrev_b32_e32 v118, 16, v80
	v_and_b32_e32 v119, 0xffff0000, v80
	v_mul_f32_e32 v120, v125, v118
	v_mul_f32_e32 v121, v125, v119
	v_exp_f32_e32 v120, v120
	v_exp_f32_e32 v121, v121
	v_mul_f32_e32 v48, v48, v150
	v_add_f32_e32 v120, 1.0, v120
	v_add_f32_e32 v121, 1.0, v121
	v_rcp_f32_e32 v120, v120
	v_rcp_f32_e32 v121, v121
	v_mul_f32_e32 v64, v64, v150
	v_mul_f32_e32 v48, v48, v96
	v_mul_f32_e32 v118, v118, v120
	v_mul_f32_e32 v119, v119, v121
	v_mul_f32_e32 v64, v64, v97
	v_mul_f32_e32 v48, v48, v118
	v_mul_f32_e32 v64, v64, v119
	v_cvt_pk_bf16_f32 v154, v48, v64
	v_lshlrev_b32_e32 v118, 16, v81
	v_and_b32_e32 v119, 0xffff0000, v81
	v_mul_f32_e32 v120, v125, v118
	v_mul_f32_e32 v121, v125, v119
	v_exp_f32_e32 v120, v120
	v_exp_f32_e32 v121, v121
	v_mul_f32_e32 v49, v49, v150
	v_add_f32_e32 v120, 1.0, v120
	v_add_f32_e32 v121, 1.0, v121
	v_rcp_f32_e32 v120, v120
	v_rcp_f32_e32 v121, v121
	v_mul_f32_e32 v65, v65, v150
	v_mul_f32_e32 v49, v49, v98
	v_mul_f32_e32 v118, v118, v120
	v_mul_f32_e32 v119, v119, v121
	v_mul_f32_e32 v65, v65, v99
	v_mul_f32_e32 v49, v49, v118
	v_mul_f32_e32 v65, v65, v119
	v_cvt_pk_bf16_f32 v155, v49, v65
	v_lshlrev_b32_e32 v118, 16, v82
	v_and_b32_e32 v119, 0xffff0000, v82
	v_mul_f32_e32 v120, v125, v118
	v_mul_f32_e32 v121, v125, v119
	v_exp_f32_e32 v120, v120
	v_exp_f32_e32 v121, v121
	v_mul_f32_e32 v50, v50, v150
	v_add_f32_e32 v120, 1.0, v120
	v_add_f32_e32 v121, 1.0, v121
	v_rcp_f32_e32 v120, v120
	v_rcp_f32_e32 v121, v121
	v_mul_f32_e32 v66, v66, v150
	v_mul_f32_e32 v50, v50, v100
	v_mul_f32_e32 v118, v118, v120
	v_mul_f32_e32 v119, v119, v121
	v_mul_f32_e32 v66, v66, v101
	v_mul_f32_e32 v50, v50, v118
	v_mul_f32_e32 v66, v66, v119
	v_cvt_pk_bf16_f32 v156, v50, v66
	v_lshlrev_b32_e32 v118, 16, v83
	v_and_b32_e32 v119, 0xffff0000, v83
	v_mul_f32_e32 v120, v125, v118
	v_mul_f32_e32 v121, v125, v119
	v_exp_f32_e32 v120, v120
	v_exp_f32_e32 v121, v121
	v_mul_f32_e32 v51, v51, v150
	v_add_f32_e32 v120, 1.0, v120
	v_add_f32_e32 v121, 1.0, v121
	v_rcp_f32_e32 v120, v120
	v_rcp_f32_e32 v121, v121
	v_mul_f32_e32 v67, v67, v150
	v_mul_f32_e32 v51, v51, v102
	v_mul_f32_e32 v118, v118, v120
	v_mul_f32_e32 v119, v119, v121
	v_mul_f32_e32 v67, v67, v103
	v_mul_f32_e32 v51, v51, v118
	v_mul_f32_e32 v67, v67, v119
	v_cvt_pk_bf16_f32 v157, v51, v67
	global_store_dwordx4 v110, v[154:157], s[42:43]
	v_lshlrev_b32_e32 v118, 16, v84
	v_and_b32_e32 v119, 0xffff0000, v84
	v_mul_f32_e32 v120, v125, v118
	v_mul_f32_e32 v121, v125, v119
	v_exp_f32_e32 v120, v120
	v_exp_f32_e32 v121, v121
	v_mul_f32_e32 v52, v52, v151
	v_add_f32_e32 v120, 1.0, v120
	v_add_f32_e32 v121, 1.0, v121
	v_rcp_f32_e32 v120, v120
	v_rcp_f32_e32 v121, v121
	v_mul_f32_e32 v68, v68, v151
	v_mul_f32_e32 v52, v52, v96
	v_mul_f32_e32 v118, v118, v120
	v_mul_f32_e32 v119, v119, v121
	v_mul_f32_e32 v68, v68, v97
	v_mul_f32_e32 v52, v52, v118
	v_mul_f32_e32 v68, v68, v119
	v_cvt_pk_bf16_f32 v158, v52, v68
	v_lshlrev_b32_e32 v118, 16, v85
	v_and_b32_e32 v119, 0xffff0000, v85
	v_mul_f32_e32 v120, v125, v118
	v_mul_f32_e32 v121, v125, v119
	v_exp_f32_e32 v120, v120
	v_exp_f32_e32 v121, v121
	v_mul_f32_e32 v53, v53, v151
	v_add_f32_e32 v120, 1.0, v120
	v_add_f32_e32 v121, 1.0, v121
	v_rcp_f32_e32 v120, v120
	v_rcp_f32_e32 v121, v121
	v_mul_f32_e32 v69, v69, v151
	v_mul_f32_e32 v53, v53, v98
	v_mul_f32_e32 v118, v118, v120
	v_mul_f32_e32 v119, v119, v121
	v_mul_f32_e32 v69, v69, v99
	v_mul_f32_e32 v53, v53, v118
	v_mul_f32_e32 v69, v69, v119
	v_cvt_pk_bf16_f32 v159, v53, v69
	v_lshlrev_b32_e32 v118, 16, v86
	v_and_b32_e32 v119, 0xffff0000, v86
	v_mul_f32_e32 v120, v125, v118
	v_mul_f32_e32 v121, v125, v119
	v_exp_f32_e32 v120, v120
	v_exp_f32_e32 v121, v121
	v_mul_f32_e32 v54, v54, v151
	v_add_f32_e32 v120, 1.0, v120
	v_add_f32_e32 v121, 1.0, v121
	v_rcp_f32_e32 v120, v120
	v_rcp_f32_e32 v121, v121
	v_mul_f32_e32 v70, v70, v151
	v_mul_f32_e32 v54, v54, v100
	v_mul_f32_e32 v118, v118, v120
	v_mul_f32_e32 v119, v119, v121
	v_mul_f32_e32 v70, v70, v101
	v_mul_f32_e32 v54, v54, v118
	v_mul_f32_e32 v70, v70, v119
	v_cvt_pk_bf16_f32 v160, v54, v70
	v_lshlrev_b32_e32 v118, 16, v87
	v_and_b32_e32 v119, 0xffff0000, v87
	v_mul_f32_e32 v120, v125, v118
	v_mul_f32_e32 v121, v125, v119
	v_exp_f32_e32 v120, v120
	v_exp_f32_e32 v121, v121
	v_mul_f32_e32 v55, v55, v151
	v_add_f32_e32 v120, 1.0, v120
	v_add_f32_e32 v121, 1.0, v121
	v_rcp_f32_e32 v120, v120
	v_rcp_f32_e32 v121, v121
	v_mul_f32_e32 v71, v71, v151
	v_mul_f32_e32 v55, v55, v102
	v_mul_f32_e32 v118, v118, v120
	v_mul_f32_e32 v119, v119, v121
	v_mul_f32_e32 v71, v71, v103
	v_mul_f32_e32 v55, v55, v118
	v_mul_f32_e32 v71, v71, v119
	v_cvt_pk_bf16_f32 v161, v55, v71
	global_store_dwordx4 v111, v[158:161], s[42:43]
	v_lshlrev_b32_e32 v118, 16, v88
	v_and_b32_e32 v119, 0xffff0000, v88
	v_mul_f32_e32 v120, v125, v118
	v_mul_f32_e32 v121, v125, v119
; DI u32x4 pack8(const float* o) { u32x4 r; r.x = pk2(o[0], o[1]); r.y = pk2(o[2], o[3]); r.z = pk2(o[4], o[5]); r.w = pk2(o[6], o[7]); return r; }
; DI float siluf(float x) { return x * __builtin_amdgcn_rcpf(1.f + __expf(-x)); }
; DI void finish_item(const P& p, int l, int r16) {
;     ...
;         for (int e = 0; e < 8; ++e) o[e] = o[e] * rstd * (e < 4 ? nw0[e & 3] : nw1[e & 3]) * siluf(gt[e]);
;         *(u32x4*)(Y + (size_t)(row0 + k) * DM + 512 * mx + chn) = pack8(o);
;     }
; }
; DI void xcd_barrier(const XcdBarrier& b) {
;     asm volatile("s_waitcnt vmcnt(0)" ::: "memory");
;     __syncthreads();
;     if (threadIdx.x == 0) {
;         unsigned* bar = b.bar;
;         __builtin_amdgcn_s_waitcnt(0);
;         unsigned nloc = b.st[0], nx = b.st[1];
;         if (nloc == 0u) { xcd_barrier_complete(bar, b.x, nloc, nx); b.st[0] = nloc; b.st[1] = nx; }
	v_exp_f32_e32 v120, v120
	v_exp_f32_e32 v121, v121
	v_mul_f32_e32 v56, v56, v152
	v_add_f32_e32 v120, 1.0, v120
	v_add_f32_e32 v121, 1.0, v121
	v_rcp_f32_e32 v120, v120
	v_rcp_f32_e32 v121, v121
	v_mul_f32_e32 v72, v72, v152
	v_mul_f32_e32 v56, v56, v96
	v_mul_f32_e32 v118, v118, v120
	v_mul_f32_e32 v119, v119, v121
	v_mul_f32_e32 v72, v72, v97
	v_mul_f32_e32 v56, v56, v118
	v_mul_f32_e32 v72, v72, v119
	v_cvt_pk_bf16_f32 v154, v56, v72
	v_lshlrev_b32_e32 v118, 16, v89
	v_and_b32_e32 v119, 0xffff0000, v89
	v_mul_f32_e32 v120, v125, v118
	v_mul_f32_e32 v121, v125, v119
	v_exp_f32_e32 v120, v120
	v_exp_f32_e32 v121, v121
	v_mul_f32_e32 v57, v57, v152
	v_add_f32_e32 v120, 1.0, v120
	v_add_f32_e32 v121, 1.0, v121
	v_rcp_f32_e32 v120, v120
	v_rcp_f32_e32 v121, v121
	v_mul_f32_e32 v73, v73, v152
	v_mul_f32_e32 v57, v57, v98
	v_mul_f32_e32 v118, v118, v120
	v_mul_f32_e32 v119, v119, v121
	v_mul_f32_e32 v73, v73, v99
	v_mul_f32_e32 v57, v57, v118
	v_mul_f32_e32 v73, v73, v119
	v_cvt_pk_bf16_f32 v155, v57, v73
	v_lshlrev_b32_e32 v118, 16, v90
	v_and_b32_e32 v119, 0xffff0000, v90
	v_mul_f32_e32 v120, v125, v118
	v_mul_f32_e32 v121, v125, v119
	v_exp_f32_e32 v120, v120
	v_exp_f32_e32 v121, v121
	v_mul_f32_e32 v58, v58, v152
	v_add_f32_e32 v120, 1.0, v120
	v_add_f32_e32 v121, 1.0, v121
	v_rcp_f32_e32 v120, v120
	v_rcp_f32_e32 v121, v121
	v_mul_f32_e32 v74, v74, v152
	v_mul_f32_e32 v58, v58, v100
	v_mul_f32_e32 v118, v118, v120
	v_mul_f32_e32 v119, v119, v121
	v_mul_f32_e32 v74, v74, v101
	v_mul_f32_e32 v58, v58, v118
	v_mul_f32_e32 v74, v74, v119
	v_cvt_pk_bf16_f32 v156, v58, v74
	v_lshlrev_b32_e32 v118, 16, v91
	v_and_b32_e32 v119, 0xffff0000, v91
	v_mul_f32_e32 v120, v125, v118
	v_mul_f32_e32 v121, v125, v119
	v_exp_f32_e32 v120, v120
	v_exp_f32_e32 v121, v121
	v_mul_f32_e32 v59, v59, v152
	v_add_f32_e32 v120, 1.0, v120
	v_add_f32_e32 v121, 1.0, v121
	v_rcp_f32_e32 v120, v120
	v_rcp_f32_e32 v121, v121
	v_mul_f32_e32 v75, v75, v152
	v_mul_f32_e32 v59, v59, v102
	v_mul_f32_e32 v118, v118, v120
	v_mul_f32_e32 v119, v119, v121
	v_mul_f32_e32 v75, v75, v103
	v_mul_f32_e32 v59, v59, v118
	v_mul_f32_e32 v75, v75, v119
	v_cvt_pk_bf16_f32 v157, v59, v75
	global_store_dwordx4 v112, v[154:157], s[42:43]
	v_lshlrev_b32_e32 v118, 16, v92
	v_and_b32_e32 v119, 0xffff0000, v92
	v_mul_f32_e32 v120, v125, v118
	v_mul_f32_e32 v121, v125, v119
	v_exp_f32_e32 v120, v120
	v_exp_f32_e32 v121, v121
	v_mul_f32_e32 v60, v60, v153
	v_add_f32_e32 v120, 1.0, v120
	v_add_f32_e32 v121, 1.0, v121
	v_rcp_f32_e32 v120, v120
	v_rcp_f32_e32 v121, v121
	v_mul_f32_e32 v76, v76, v153
	v_mul_f32_e32 v60, v60, v96
	v_mul_f32_e32 v118, v118, v120
	v_mul_f32_e32 v119, v119, v121
	v_mul_f32_e32 v76, v76, v97
	v_mul_f32_e32 v60, v60, v118
	v_mul_f32_e32 v76, v76, v119
	v_cvt_pk_bf16_f32 v158, v60, v76
	v_lshlrev_b32_e32 v118, 16, v93
	v_and_b32_e32 v119, 0xffff0000, v93
	v_mul_f32_e32 v120, v125, v118
	v_mul_f32_e32 v121, v125, v119
	v_exp_f32_e32 v120, v120
	v_exp_f32_e32 v121, v121
	v_mul_f32_e32 v61, v61, v153
	v_add_f32_e32 v120, 1.0, v120
	v_add_f32_e32 v121, 1.0, v121
	v_rcp_f32_e32 v120, v120
	v_rcp_f32_e32 v121, v121
	v_mul_f32_e32 v77, v77, v153
	v_mul_f32_e32 v61, v61, v98
	v_mul_f32_e32 v118, v118, v120
	v_mul_f32_e32 v119, v119, v121
	v_mul_f32_e32 v77, v77, v99
	v_mul_f32_e32 v61, v61, v118
	v_mul_f32_e32 v77, v77, v119
	v_cvt_pk_bf16_f32 v159, v61, v77
	v_lshlrev_b32_e32 v118, 16, v94
	v_and_b32_e32 v119, 0xffff0000, v94
	v_mul_f32_e32 v120, v125, v118
	v_mul_f32_e32 v121, v125, v119
	v_exp_f32_e32 v120, v120
	v_exp_f32_e32 v121, v121
	v_mul_f32_e32 v62, v62, v153
	v_add_f32_e32 v120, 1.0, v120
	v_add_f32_e32 v121, 1.0, v121
	v_rcp_f32_e32 v120, v120
	v_rcp_f32_e32 v121, v121
	v_mul_f32_e32 v78, v78, v153
	v_mul_f32_e32 v62, v62, v100
	v_mul_f32_e32 v118, v118, v120
	v_mul_f32_e32 v119, v119, v121
	v_mul_f32_e32 v78, v78, v101
	v_mul_f32_e32 v62, v62, v118
	v_mul_f32_e32 v78, v78, v119
	v_cvt_pk_bf16_f32 v160, v62, v78
	v_lshlrev_b32_e32 v118, 16, v95
	v_and_b32_e32 v119, 0xffff0000, v95
	v_mul_f32_e32 v120, v125, v118
	v_mul_f32_e32 v121, v125, v119
	v_exp_f32_e32 v120, v120
	v_exp_f32_e32 v121, v121
	v_mul_f32_e32 v63, v63, v153
	v_add_f32_e32 v120, 1.0, v120
	v_add_f32_e32 v121, 1.0, v121
	v_rcp_f32_e32 v120, v120
	v_rcp_f32_e32 v121, v121
	v_mul_f32_e32 v79, v79, v153
	v_mul_f32_e32 v63, v63, v102
	v_mul_f32_e32 v118, v118, v120
	v_mul_f32_e32 v119, v119, v121
	v_mul_f32_e32 v79, v79, v103
	v_mul_f32_e32 v63, v63, v118
	v_mul_f32_e32 v79, v79, v119
	v_cvt_pk_bf16_f32 v161, v63, v79
	global_store_dwordx4 v113, v[158:161], s[42:43]
	s_cmp_lt_u32 s7, s22
	s_cbranch_scc0 .Lfin_done
	s_mov_b32 s24, s7
	s_add_u32 s7, s7, s6
	s_branch .Lfin_it0
.Lfin_done:
.LBB0_682:
	s_waitcnt vmcnt(0)
	s_barrier
	s_mov_b64 s[0:1], exec
	v_readlane_b32 s2, v253, 1
	v_readlane_b32 s3, v253, 2
	s_and_b64 s[2:3], s[0:1], s[2:3]
	s_mov_b64 s[8:9], 0x6c3c000
	s_mov_b64 exec, s[2:3]
	s_cbranch_execz .LBB0_730
	v_readlane_b32 s2, v254, 32
	s_waitcnt vmcnt(0) expcnt(0) lgkmcnt(0)
	s_nop 0
	v_mov_b32_e32 v0, s2
	ds_read_b32 v2, v0
	v_readlane_b32 s2, v254, 33
	s_waitcnt lgkmcnt(0)
	v_cmp_ne_u32_e32 vcc, 0, v2
	v_mov_b32_e32 v0, s2
	ds_read_b32 v0, v0
	s_cbranch_vccnz .LBB0_698
	s_mov_b32 s2, 1
	s_branch .LBB0_686
